# selection bins taken from the float mantissa (2^23 bias, 1021-step scale, guard on lo*scale), paired LDS score reads
# speedup vs baseline: 1.0314x; 1.0026x over previous
; DI void lds_barrier() { asm volatile("s_waitcnt lgkmcnt(0)" ::: "memory"); __builtin_amdgcn_s_barrier(); asm volatile("" ::: "memory"); }
; DI float ord2f(unsigned k) { return __uint_as_float((k & 0x80000000u) ? (k ^ 0x80000000u) : ~k); }
; DI void selectA_item(const Params& p, int item, int next_item, char* lds, bf16x8 (&qf)[4], float (&wq)[16]) {
;     ...
;     const float lo = ord2f(mm[g * 2]), hi = ord2f(mm[g * 2 + 1]);
;     const float scale = (hi > lo) ? 1023.f / (hi - lo) : 0.f;
;     for (int i = gt; i < 1024; i += 128) histq[i] = 0;
;     if (gt == 0) { mq[0] = 0; mq[6] = 0; }
;     lds_barrier();
;     float uu[64];
; #pragma unroll
;     for (int i = 0; i < 64; ++i) { const int idx = gt + 128 * i; const float v = (idx < n) ? scq[idx] : lo; const float u = (v - lo) * scale; uu[i] = u;
;       if (big && idx < n) { int bb = (int)u; bb = bb > 1023 ? 1023 : bb; atomicAdd(&histq[bb], 1); } }
.Lsel_big:
	s_lshl_b32 s2, s37, 3
	s_add_i32 s2, s2, 0x24060
	v_mov_b32_e32 v0, s2
	ds_read_b64 v[2:3], v0
	s_lshl_b32 s3, s37, 2
	s_add_i32 s3, s3, 0x25180
	v_mov_b32_e32 v1, s3
	ds_read_b32 v7, v1
	v_lshl_add_u32 v241, v183, 2, 0
	v_add_u32_e32 v241, 0x25200, v241
	s_waitcnt lgkmcnt(0)
	v_ashrrev_i32_e32 v1, 31, v7
	v_and_b32_e32 v1, 0x7fffffff, v1
	v_not_b32_e32 v1, v1
	v_xor_b32_e32 v7, v7, v1
	v_ashrrev_i32_e32 v4, 31, v2
	v_ashrrev_i32_e32 v5, 31, v3
	v_and_b32_e32 v4, 0x7fffffff, v4
	v_and_b32_e32 v5, 0x7fffffff, v5
	v_not_b32_e32 v4, v4
	v_not_b32_e32 v5, v5
	v_xor_b32_e32 v192, v2, v4
	v_xor_b32_e32 v5, v3, v5
	v_sub_f32_e32 v6, v5, v192
	v_cmp_gt_f32_e32 vcc, v5, v192
	v_rcp_f32_e32 v6, v6
	s_nop 1
	v_mul_f32_e32 v6, 0x447f4000, v6
	v_cndmask_b32_e32 v193, 0, v6, vcc
	s_nop 0
	v_mul_f32_e32 v194, v192, v193
	s_sub_u32 s10, s41, 0x2c000000
	v_mov_b32_e32 v6, 0x45800000
	v_cmp_lt_f32_e64 s[8:9], |v194|, v6
	s_nop 1
	s_cmp_eq_u64 s[8:9], 0
	v_sub_f32_e32 v194, 0x4b000001, v194
	s_nop 0
	v_fma_f32 v240, v7, v193, v194
	s_cbranch_scc1 .Lsel_guard_fb
.Lsel_B_0:
	s_cmp_lt_u32 s40, 0x400
	s_cbranch_scc1 .Lsel_B_0_part
	ds_read2st64_b32 v[8:9], v181 offset0:0 offset1:2
	ds_read2st64_b32 v[10:11], v181 offset0:4 offset1:6
	ds_read2st64_b32 v[12:13], v181 offset0:8 offset1:10
	ds_read2st64_b32 v[14:15], v181 offset0:12 offset1:14
	s_waitcnt lgkmcnt(3)
	v_fma_f32 v116, v8, v193, v194
	v_fma_f32 v117, v9, v193, v194
	v_cmp_ge_f32_e32 vcc, v116, v240
	v_cmp_ge_f32_e64 s[8:9], v117, v240
	v_lshl_add_u32 v16, v116, 2, s10
	v_lshl_add_u32 v17, v117, 2, s10
	v_cndmask_b32_e32 v16, v241, v16, vcc
	v_cndmask_b32_e64 v17, v241, v17, s[8:9]
	ds_add_u32 v16, v206
	ds_add_u32 v17, v206
	s_waitcnt lgkmcnt(4)
	v_fma_f32 v118, v10, v193, v194
	v_fma_f32 v119, v11, v193, v194
	v_cmp_ge_f32_e32 vcc, v118, v240
	v_cmp_ge_f32_e64 s[8:9], v119, v240
	v_lshl_add_u32 v18, v118, 2, s10
	v_lshl_add_u32 v19, v119, 2, s10
	v_cndmask_b32_e32 v18, v241, v18, vcc
	v_cndmask_b32_e64 v19, v241, v19, s[8:9]
	ds_add_u32 v18, v206
	ds_add_u32 v19, v206
	s_waitcnt lgkmcnt(5)
	v_fma_f32 v120, v12, v193, v194
	v_fma_f32 v121, v13, v193, v194
	v_cmp_ge_f32_e32 vcc, v120, v240
	v_cmp_ge_f32_e64 s[8:9], v121, v240
	v_lshl_add_u32 v20, v120, 2, s10
	v_lshl_add_u32 v21, v121, 2, s10
	v_cndmask_b32_e32 v20, v241, v20, vcc
	v_cndmask_b32_e64 v21, v241, v21, s[8:9]
	ds_add_u32 v20, v206
	ds_add_u32 v21, v206
	s_waitcnt lgkmcnt(6)
	v_fma_f32 v122, v14, v193, v194
	v_fma_f32 v123, v15, v193, v194
	v_cmp_ge_f32_e32 vcc, v122, v240
	v_cmp_ge_f32_e64 s[8:9], v123, v240
	v_lshl_add_u32 v22, v122, 2, s10
	v_lshl_add_u32 v23, v123, 2, s10
	v_cndmask_b32_e32 v22, v241, v22, vcc
	v_cndmask_b32_e64 v23, v241, v23, s[8:9]
	ds_add_u32 v22, v206
	ds_add_u32 v23, v206
.Lsel_B_1:
	s_cmp_le_u32 s40, 0x400
	s_cbranch_scc1 .Lsel_B_done
	s_cmp_lt_u32 s40, 0x800
	s_cbranch_scc1 .Lsel_B_1_part
	ds_read2st64_b32 v[8:9], v181 offset0:16 offset1:18
	ds_read2st64_b32 v[10:11], v181 offset0:20 offset1:22
	ds_read2st64_b32 v[12:13], v181 offset0:24 offset1:26
	ds_read2st64_b32 v[14:15], v181 offset0:28 offset1:30
	s_waitcnt lgkmcnt(3)
	v_fma_f32 v124, v8, v193, v194
	v_fma_f32 v125, v9, v193, v194
	v_cmp_ge_f32_e32 vcc, v124, v240
	v_cmp_ge_f32_e64 s[8:9], v125, v240
	v_lshl_add_u32 v16, v124, 2, s10
	v_lshl_add_u32 v17, v125, 2, s10
	v_cndmask_b32_e32 v16, v241, v16, vcc
	v_cndmask_b32_e64 v17, v241, v17, s[8:9]
	ds_add_u32 v16, v206
	ds_add_u32 v17, v206
	s_waitcnt lgkmcnt(4)
	v_fma_f32 v126, v10, v193, v194
	v_fma_f32 v127, v11, v193, v194
	v_cmp_ge_f32_e32 vcc, v126, v240
	v_cmp_ge_f32_e64 s[8:9], v127, v240
	v_lshl_add_u32 v18, v126, 2, s10
	v_lshl_add_u32 v19, v127, 2, s10
	v_cndmask_b32_e32 v18, v241, v18, vcc
	v_cndmask_b32_e64 v19, v241, v19, s[8:9]
	ds_add_u32 v18, v206
	ds_add_u32 v19, v206
	s_waitcnt lgkmcnt(5)
	v_fma_f32 v128, v12, v193, v194
	v_fma_f32 v129, v13, v193, v194
	v_cmp_ge_f32_e32 vcc, v128, v240
	v_cmp_ge_f32_e64 s[8:9], v129, v240
	v_lshl_add_u32 v20, v128, 2, s10
	v_lshl_add_u32 v21, v129, 2, s10
	v_cndmask_b32_e32 v20, v241, v20, vcc
	v_cndmask_b32_e64 v21, v241, v21, s[8:9]
	ds_add_u32 v20, v206
	ds_add_u32 v21, v206
	s_waitcnt lgkmcnt(6)
	v_fma_f32 v130, v14, v193, v194
	v_fma_f32 v131, v15, v193, v194
	v_cmp_ge_f32_e32 vcc, v130, v240
	v_cmp_ge_f32_e64 s[8:9], v131, v240
	v_lshl_add_u32 v22, v130, 2, s10
	v_lshl_add_u32 v23, v131, 2, s10
	v_cndmask_b32_e32 v22, v241, v22, vcc
	v_cndmask_b32_e64 v23, v241, v23, s[8:9]
	ds_add_u32 v22, v206
	ds_add_u32 v23, v206
.Lsel_B_2:
	s_cmp_le_u32 s40, 0x800
	s_cbranch_scc1 .Lsel_B_done
	s_cmp_lt_u32 s40, 0xc00
	s_cbranch_scc1 .Lsel_B_2_part
	ds_read2st64_b32 v[8:9], v181 offset0:32 offset1:34
	ds_read2st64_b32 v[10:11], v181 offset0:36 offset1:38
	ds_read2st64_b32 v[12:13], v181 offset0:40 offset1:42
	ds_read2st64_b32 v[14:15], v181 offset0:44 offset1:46
	s_waitcnt lgkmcnt(3)
	v_fma_f32 v132, v8, v193, v194
	v_fma_f32 v133, v9, v193, v194
	v_cmp_ge_f32_e32 vcc, v132, v240
	v_cmp_ge_f32_e64 s[8:9], v133, v240
	v_lshl_add_u32 v16, v132, 2, s10
	v_lshl_add_u32 v17, v133, 2, s10
	v_cndmask_b32_e32 v16, v241, v16, vcc
	v_cndmask_b32_e64 v17, v241, v17, s[8:9]
	ds_add_u32 v16, v206
	ds_add_u32 v17, v206
	s_waitcnt lgkmcnt(4)
	v_fma_f32 v134, v10, v193, v194
	v_fma_f32 v135, v11, v193, v194
	v_cmp_ge_f32_e32 vcc, v134, v240
	v_cmp_ge_f32_e64 s[8:9], v135, v240
	v_lshl_add_u32 v18, v134, 2, s10
	v_lshl_add_u32 v19, v135, 2, s10
	v_cndmask_b32_e32 v18, v241, v18, vcc
	v_cndmask_b32_e64 v19, v241, v19, s[8:9]
	ds_add_u32 v18, v206
	ds_add_u32 v19, v206
	s_waitcnt lgkmcnt(5)
	v_fma_f32 v136, v12, v193, v194
	v_fma_f32 v137, v13, v193, v194
	v_cmp_ge_f32_e32 vcc, v136, v240
	v_cmp_ge_f32_e64 s[8:9], v137, v240
	v_lshl_add_u32 v20, v136, 2, s10
	v_lshl_add_u32 v21, v137, 2, s10
	v_cndmask_b32_e32 v20, v241, v20, vcc
	v_cndmask_b32_e64 v21, v241, v21, s[8:9]
	ds_add_u32 v20, v206
	ds_add_u32 v21, v206
	s_waitcnt lgkmcnt(6)
	v_fma_f32 v138, v14, v193, v194
	v_fma_f32 v139, v15, v193, v194
	v_cmp_ge_f32_e32 vcc, v138, v240
	v_cmp_ge_f32_e64 s[8:9], v139, v240
	v_lshl_add_u32 v22, v138, 2, s10
	v_lshl_add_u32 v23, v139, 2, s10
	v_cndmask_b32_e32 v22, v241, v22, vcc
	v_cndmask_b32_e64 v23, v241, v23, s[8:9]
	ds_add_u32 v22, v206
	ds_add_u32 v23, v206
; DI void selectA_item(const Params& p, int item, int next_item, char* lds, bf16x8 (&qf)[4], float (&wq)[16]) {
;     ...
; #pragma unroll
;     for (int i = 0; i < 64; ++i) { const int idx = gt + 128 * i; const float v = (idx < n) ? scq[idx] : lo; const float u = (v - lo) * scale; uu[i] = u;
;       if (big && idx < n) { int bb = (int)u; bb = bb > 1023 ? 1023 : bb; atomicAdd(&histq[bb], 1); } }
.Lsel_B_3:
	s_cmp_le_u32 s40, 0xc00
	s_cbranch_scc1 .Lsel_B_done
	s_cmp_lt_u32 s40, 0x1000
	s_cbranch_scc1 .Lsel_B_3_part
	ds_read2st64_b32 v[8:9], v181 offset0:48 offset1:50
	ds_read2st64_b32 v[10:11], v181 offset0:52 offset1:54
	ds_read2st64_b32 v[12:13], v181 offset0:56 offset1:58
	ds_read2st64_b32 v[14:15], v181 offset0:60 offset1:62
	s_waitcnt lgkmcnt(3)
	v_fma_f32 v140, v8, v193, v194
	v_fma_f32 v141, v9, v193, v194
	v_cmp_ge_f32_e32 vcc, v140, v240
	v_cmp_ge_f32_e64 s[8:9], v141, v240
	v_lshl_add_u32 v16, v140, 2, s10
	v_lshl_add_u32 v17, v141, 2, s10
	v_cndmask_b32_e32 v16, v241, v16, vcc
	v_cndmask_b32_e64 v17, v241, v17, s[8:9]
	ds_add_u32 v16, v206
	ds_add_u32 v17, v206
	s_waitcnt lgkmcnt(4)
	v_fma_f32 v142, v10, v193, v194
	v_fma_f32 v143, v11, v193, v194
	v_cmp_ge_f32_e32 vcc, v142, v240
	v_cmp_ge_f32_e64 s[8:9], v143, v240
	v_lshl_add_u32 v18, v142, 2, s10
	v_lshl_add_u32 v19, v143, 2, s10
	v_cndmask_b32_e32 v18, v241, v18, vcc
	v_cndmask_b32_e64 v19, v241, v19, s[8:9]
	ds_add_u32 v18, v206
	ds_add_u32 v19, v206
	s_waitcnt lgkmcnt(5)
	v_fma_f32 v144, v12, v193, v194
	v_fma_f32 v145, v13, v193, v194
	v_cmp_ge_f32_e32 vcc, v144, v240
	v_cmp_ge_f32_e64 s[8:9], v145, v240
	v_lshl_add_u32 v20, v144, 2, s10
	v_lshl_add_u32 v21, v145, 2, s10
	v_cndmask_b32_e32 v20, v241, v20, vcc
	v_cndmask_b32_e64 v21, v241, v21, s[8:9]
	ds_add_u32 v20, v206
	ds_add_u32 v21, v206
	s_waitcnt lgkmcnt(6)
	v_fma_f32 v146, v14, v193, v194
	v_fma_f32 v147, v15, v193, v194
	v_cmp_ge_f32_e32 vcc, v146, v240
	v_cmp_ge_f32_e64 s[8:9], v147, v240
	v_lshl_add_u32 v22, v146, 2, s10
	v_lshl_add_u32 v23, v147, 2, s10
	v_cndmask_b32_e32 v22, v241, v22, vcc
	v_cndmask_b32_e64 v23, v241, v23, s[8:9]
	ds_add_u32 v22, v206
	ds_add_u32 v23, v206
.Lsel_B_4:
	s_cmp_le_u32 s40, 0x1000
	s_cbranch_scc1 .Lsel_B_done
	s_cmp_lt_u32 s40, 0x1400
	s_cbranch_scc1 .Lsel_B_4_part
	ds_read2st64_b32 v[8:9], v181 offset0:64 offset1:66
	ds_read2st64_b32 v[10:11], v181 offset0:68 offset1:70
	ds_read2st64_b32 v[12:13], v181 offset0:72 offset1:74
	ds_read2st64_b32 v[14:15], v181 offset0:76 offset1:78
	s_waitcnt lgkmcnt(3)
	v_fma_f32 v148, v8, v193, v194
	v_fma_f32 v149, v9, v193, v194
	v_cmp_ge_f32_e32 vcc, v148, v240
	v_cmp_ge_f32_e64 s[8:9], v149, v240
	v_lshl_add_u32 v16, v148, 2, s10
	v_lshl_add_u32 v17, v149, 2, s10
	v_cndmask_b32_e32 v16, v241, v16, vcc
	v_cndmask_b32_e64 v17, v241, v17, s[8:9]
	ds_add_u32 v16, v206
	ds_add_u32 v17, v206
	s_waitcnt lgkmcnt(4)
	v_fma_f32 v150, v10, v193, v194
	v_fma_f32 v151, v11, v193, v194
	v_cmp_ge_f32_e32 vcc, v150, v240
	v_cmp_ge_f32_e64 s[8:9], v151, v240
	v_lshl_add_u32 v18, v150, 2, s10
	v_lshl_add_u32 v19, v151, 2, s10
	v_cndmask_b32_e32 v18, v241, v18, vcc
	v_cndmask_b32_e64 v19, v241, v19, s[8:9]
	ds_add_u32 v18, v206
	ds_add_u32 v19, v206
	s_waitcnt lgkmcnt(5)
	v_fma_f32 v152, v12, v193, v194
	v_fma_f32 v153, v13, v193, v194
	v_cmp_ge_f32_e32 vcc, v152, v240
	v_cmp_ge_f32_e64 s[8:9], v153, v240
	v_lshl_add_u32 v20, v152, 2, s10
	v_lshl_add_u32 v21, v153, 2, s10
	v_cndmask_b32_e32 v20, v241, v20, vcc
	v_cndmask_b32_e64 v21, v241, v21, s[8:9]
	ds_add_u32 v20, v206
	ds_add_u32 v21, v206
	s_waitcnt lgkmcnt(6)
	v_fma_f32 v154, v14, v193, v194
	v_fma_f32 v155, v15, v193, v194
	v_cmp_ge_f32_e32 vcc, v154, v240
	v_cmp_ge_f32_e64 s[8:9], v155, v240
	v_lshl_add_u32 v22, v154, 2, s10
	v_lshl_add_u32 v23, v155, 2, s10
	v_cndmask_b32_e32 v22, v241, v22, vcc
	v_cndmask_b32_e64 v23, v241, v23, s[8:9]
	ds_add_u32 v22, v206
	ds_add_u32 v23, v206
.Lsel_B_5:
	s_cmp_le_u32 s40, 0x1400
	s_cbranch_scc1 .Lsel_B_done
	s_cmp_lt_u32 s40, 0x1800
	s_cbranch_scc1 .Lsel_B_5_part
	ds_read2st64_b32 v[8:9], v181 offset0:80 offset1:82
	ds_read2st64_b32 v[10:11], v181 offset0:84 offset1:86
	ds_read2st64_b32 v[12:13], v181 offset0:88 offset1:90
	ds_read2st64_b32 v[14:15], v181 offset0:92 offset1:94
	s_waitcnt lgkmcnt(3)
	v_fma_f32 v156, v8, v193, v194
	v_fma_f32 v157, v9, v193, v194
	v_cmp_ge_f32_e32 vcc, v156, v240
	v_cmp_ge_f32_e64 s[8:9], v157, v240
	v_lshl_add_u32 v16, v156, 2, s10
	v_lshl_add_u32 v17, v157, 2, s10
	v_cndmask_b32_e32 v16, v241, v16, vcc
	v_cndmask_b32_e64 v17, v241, v17, s[8:9]
	ds_add_u32 v16, v206
	ds_add_u32 v17, v206
	s_waitcnt lgkmcnt(4)
	v_fma_f32 v158, v10, v193, v194
	v_fma_f32 v159, v11, v193, v194
	v_cmp_ge_f32_e32 vcc, v158, v240
	v_cmp_ge_f32_e64 s[8:9], v159, v240
	v_lshl_add_u32 v18, v158, 2, s10
	v_lshl_add_u32 v19, v159, 2, s10
	v_cndmask_b32_e32 v18, v241, v18, vcc
	v_cndmask_b32_e64 v19, v241, v19, s[8:9]
	ds_add_u32 v18, v206
	ds_add_u32 v19, v206
	s_waitcnt lgkmcnt(5)
	v_fma_f32 v160, v12, v193, v194
	v_fma_f32 v161, v13, v193, v194
	v_cmp_ge_f32_e32 vcc, v160, v240
	v_cmp_ge_f32_e64 s[8:9], v161, v240
	v_lshl_add_u32 v20, v160, 2, s10
	v_lshl_add_u32 v21, v161, 2, s10
	v_cndmask_b32_e32 v20, v241, v20, vcc
	v_cndmask_b32_e64 v21, v241, v21, s[8:9]
	ds_add_u32 v20, v206
	ds_add_u32 v21, v206
	s_waitcnt lgkmcnt(6)
	v_fma_f32 v162, v14, v193, v194
	v_fma_f32 v163, v15, v193, v194
	v_cmp_ge_f32_e32 vcc, v162, v240
	v_cmp_ge_f32_e64 s[8:9], v163, v240
	v_lshl_add_u32 v22, v162, 2, s10
	v_lshl_add_u32 v23, v163, 2, s10
	v_cndmask_b32_e32 v22, v241, v22, vcc
	v_cndmask_b32_e64 v23, v241, v23, s[8:9]
	ds_add_u32 v22, v206
	ds_add_u32 v23, v206
; DI void selectA_item(const Params& p, int item, int next_item, char* lds, bf16x8 (&qf)[4], float (&wq)[16]) {
;     ...
; #pragma unroll
;     for (int i = 0; i < 64; ++i) { const int idx = gt + 128 * i; const float v = (idx < n) ? scq[idx] : lo; const float u = (v - lo) * scale; uu[i] = u;
;       if (big && idx < n) { int bb = (int)u; bb = bb > 1023 ? 1023 : bb; atomicAdd(&histq[bb], 1); } }
.Lsel_B_6:
	s_cmp_le_u32 s40, 0x1800
	s_cbranch_scc1 .Lsel_B_done
	s_cmp_lt_u32 s40, 0x1c00
	s_cbranch_scc1 .Lsel_B_6_part
	ds_read2st64_b32 v[8:9], v181 offset0:96 offset1:98
	ds_read2st64_b32 v[10:11], v181 offset0:100 offset1:102
	ds_read2st64_b32 v[12:13], v181 offset0:104 offset1:106
	ds_read2st64_b32 v[14:15], v181 offset0:108 offset1:110
	s_waitcnt lgkmcnt(3)
	v_fma_f32 v164, v8, v193, v194
	v_fma_f32 v165, v9, v193, v194
	v_cmp_ge_f32_e32 vcc, v164, v240
	v_cmp_ge_f32_e64 s[8:9], v165, v240
	v_lshl_add_u32 v16, v164, 2, s10
	v_lshl_add_u32 v17, v165, 2, s10
	v_cndmask_b32_e32 v16, v241, v16, vcc
	v_cndmask_b32_e64 v17, v241, v17, s[8:9]
	ds_add_u32 v16, v206
	ds_add_u32 v17, v206
	s_waitcnt lgkmcnt(4)
	v_fma_f32 v166, v10, v193, v194
	v_fma_f32 v167, v11, v193, v194
	v_cmp_ge_f32_e32 vcc, v166, v240
	v_cmp_ge_f32_e64 s[8:9], v167, v240
	v_lshl_add_u32 v18, v166, 2, s10
	v_lshl_add_u32 v19, v167, 2, s10
	v_cndmask_b32_e32 v18, v241, v18, vcc
	v_cndmask_b32_e64 v19, v241, v19, s[8:9]
	ds_add_u32 v18, v206
	ds_add_u32 v19, v206
	s_waitcnt lgkmcnt(5)
	v_fma_f32 v168, v12, v193, v194
	v_fma_f32 v169, v13, v193, v194
	v_cmp_ge_f32_e32 vcc, v168, v240
	v_cmp_ge_f32_e64 s[8:9], v169, v240
	v_lshl_add_u32 v20, v168, 2, s10
	v_lshl_add_u32 v21, v169, 2, s10
	v_cndmask_b32_e32 v20, v241, v20, vcc
	v_cndmask_b32_e64 v21, v241, v21, s[8:9]
	ds_add_u32 v20, v206
	ds_add_u32 v21, v206
	s_waitcnt lgkmcnt(6)
	v_fma_f32 v170, v14, v193, v194
	v_fma_f32 v171, v15, v193, v194
	v_cmp_ge_f32_e32 vcc, v170, v240
	v_cmp_ge_f32_e64 s[8:9], v171, v240
	v_lshl_add_u32 v22, v170, 2, s10
	v_lshl_add_u32 v23, v171, 2, s10
	v_cndmask_b32_e32 v22, v241, v22, vcc
	v_cndmask_b32_e64 v23, v241, v23, s[8:9]
	ds_add_u32 v22, v206
	ds_add_u32 v23, v206
.Lsel_B_7:
	s_cmp_le_u32 s40, 0x1c00
	s_cbranch_scc1 .Lsel_B_done
	s_cmp_lt_u32 s40, 0x2000
	s_cbranch_scc1 .Lsel_B_7_part
	ds_read2st64_b32 v[8:9], v181 offset0:112 offset1:114
	ds_read2st64_b32 v[10:11], v181 offset0:116 offset1:118
	ds_read2st64_b32 v[12:13], v181 offset0:120 offset1:122
	ds_read2st64_b32 v[14:15], v181 offset0:124 offset1:126
	s_waitcnt lgkmcnt(3)
	v_fma_f32 v172, v8, v193, v194
	v_fma_f32 v173, v9, v193, v194
	v_cmp_ge_f32_e32 vcc, v172, v240
	v_cmp_ge_f32_e64 s[8:9], v173, v240
	v_lshl_add_u32 v16, v172, 2, s10
	v_lshl_add_u32 v17, v173, 2, s10
	v_cndmask_b32_e32 v16, v241, v16, vcc
	v_cndmask_b32_e64 v17, v241, v17, s[8:9]
	ds_add_u32 v16, v206
	ds_add_u32 v17, v206
	s_waitcnt lgkmcnt(4)
	v_fma_f32 v174, v10, v193, v194
	v_fma_f32 v175, v11, v193, v194
	v_cmp_ge_f32_e32 vcc, v174, v240
	v_cmp_ge_f32_e64 s[8:9], v175, v240
	v_lshl_add_u32 v18, v174, 2, s10
	v_lshl_add_u32 v19, v175, 2, s10
	v_cndmask_b32_e32 v18, v241, v18, vcc
	v_cndmask_b32_e64 v19, v241, v19, s[8:9]
	ds_add_u32 v18, v206
	ds_add_u32 v19, v206
	s_waitcnt lgkmcnt(5)
	v_fma_f32 v176, v12, v193, v194
	v_fma_f32 v177, v13, v193, v194
	v_cmp_ge_f32_e32 vcc, v176, v240
	v_cmp_ge_f32_e64 s[8:9], v177, v240
	v_lshl_add_u32 v20, v176, 2, s10
	v_lshl_add_u32 v21, v177, 2, s10
	v_cndmask_b32_e32 v20, v241, v20, vcc
	v_cndmask_b32_e64 v21, v241, v21, s[8:9]
	ds_add_u32 v20, v206
	ds_add_u32 v21, v206
	s_waitcnt lgkmcnt(6)
	v_fma_f32 v178, v14, v193, v194
	v_fma_f32 v179, v15, v193, v194
	v_cmp_ge_f32_e32 vcc, v178, v240
	v_cmp_ge_f32_e64 s[8:9], v179, v240
	v_lshl_add_u32 v22, v178, 2, s10
	v_lshl_add_u32 v23, v179, 2, s10
	v_cndmask_b32_e32 v22, v241, v22, vcc
	v_cndmask_b32_e64 v23, v241, v23, s[8:9]
	ds_add_u32 v22, v206
	ds_add_u32 v23, v206
	s_branch .Lsel_B_done
.Lsel_B_0_part:
	s_mov_b32 s2, s40
	ds_read_b32 v8, v181 offset:0
	ds_read_b32 v9, v181 offset:512
	ds_read_b32 v10, v181 offset:1024
	ds_read_b32 v11, v181 offset:1536
	ds_read_b32 v12, v181 offset:2048
	ds_read_b32 v13, v181 offset:2560
	ds_read_b32 v14, v181 offset:3072
	ds_read_b32 v15, v181 offset:3584
	v_cmp_gt_i32_e64 s[66:67], s2, v180
	s_sub_i32 s3, s2, 0x80
	v_cmp_gt_i32_e64 s[68:69], s3, v180
	s_sub_i32 s3, s2, 0x100
	v_cmp_gt_i32_e64 s[70:71], s3, v180
	s_sub_i32 s3, s2, 0x180
	v_cmp_gt_i32_e64 s[72:73], s3, v180
	s_sub_i32 s3, s2, 0x200
	v_cmp_gt_i32_e64 s[74:75], s3, v180
	s_sub_i32 s3, s2, 0x280
	v_cmp_gt_i32_e64 s[76:77], s3, v180
	s_sub_i32 s3, s2, 0x300
	v_cmp_gt_i32_e64 s[78:79], s3, v180
	s_sub_i32 s3, s2, 0x380
	v_cmp_gt_i32_e64 s[80:81], s3, v180
	s_waitcnt lgkmcnt(7)
	v_fma_f32 v8, v8, v193, v194
	v_cndmask_b32_e64 v116, 0, v8, s[66:67]
	v_cmp_ge_f32_e32 vcc, v116, v240
	v_lshl_add_u32 v16, v116, 2, s10
	v_cndmask_b32_e64 v16, v205, v16, s[66:67]
	v_cndmask_b32_e32 v16, v241, v16, vcc
	ds_add_u32 v16, v206
	s_waitcnt lgkmcnt(7)
	v_fma_f32 v9, v9, v193, v194
	v_cndmask_b32_e64 v117, 0, v9, s[68:69]
	v_cmp_ge_f32_e32 vcc, v117, v240
	v_lshl_add_u32 v17, v117, 2, s10
	v_cndmask_b32_e64 v17, v205, v17, s[68:69]
	v_cndmask_b32_e32 v17, v241, v17, vcc
	ds_add_u32 v17, v206
	s_waitcnt lgkmcnt(7)
	v_fma_f32 v10, v10, v193, v194
	v_cndmask_b32_e64 v118, 0, v10, s[70:71]
	v_cmp_ge_f32_e32 vcc, v118, v240
	v_lshl_add_u32 v18, v118, 2, s10
	v_cndmask_b32_e64 v18, v205, v18, s[70:71]
	v_cndmask_b32_e32 v18, v241, v18, vcc
	ds_add_u32 v18, v206
	s_waitcnt lgkmcnt(7)
	v_fma_f32 v11, v11, v193, v194
	v_cndmask_b32_e64 v119, 0, v11, s[72:73]
	v_cmp_ge_f32_e32 vcc, v119, v240
	v_lshl_add_u32 v19, v119, 2, s10
	v_cndmask_b32_e64 v19, v205, v19, s[72:73]
	v_cndmask_b32_e32 v19, v241, v19, vcc
	ds_add_u32 v19, v206
	s_waitcnt lgkmcnt(7)
	v_fma_f32 v12, v12, v193, v194
	v_cndmask_b32_e64 v120, 0, v12, s[74:75]
	v_cmp_ge_f32_e32 vcc, v120, v240
	v_lshl_add_u32 v20, v120, 2, s10
	v_cndmask_b32_e64 v20, v205, v20, s[74:75]
	v_cndmask_b32_e32 v20, v241, v20, vcc
	ds_add_u32 v20, v206
	s_waitcnt lgkmcnt(7)
	v_fma_f32 v13, v13, v193, v194
	v_cndmask_b32_e64 v121, 0, v13, s[76:77]
	v_cmp_ge_f32_e32 vcc, v121, v240
	v_lshl_add_u32 v21, v121, 2, s10
	v_cndmask_b32_e64 v21, v205, v21, s[76:77]
	v_cndmask_b32_e32 v21, v241, v21, vcc
	ds_add_u32 v21, v206
	s_waitcnt lgkmcnt(7)
	v_fma_f32 v14, v14, v193, v194
	v_cndmask_b32_e64 v122, 0, v14, s[78:79]
	v_cmp_ge_f32_e32 vcc, v122, v240
	v_lshl_add_u32 v22, v122, 2, s10
	v_cndmask_b32_e64 v22, v205, v22, s[78:79]
	v_cndmask_b32_e32 v22, v241, v22, vcc
	ds_add_u32 v22, v206
	s_waitcnt lgkmcnt(7)
	v_fma_f32 v15, v15, v193, v194
	v_cndmask_b32_e64 v123, 0, v15, s[80:81]
	v_cmp_ge_f32_e32 vcc, v123, v240
	v_lshl_add_u32 v23, v123, 2, s10
	v_cndmask_b32_e64 v23, v205, v23, s[80:81]
	v_cndmask_b32_e32 v23, v241, v23, vcc
	ds_add_u32 v23, v206
	s_branch .Lsel_B_done
; DI void selectA_item(const Params& p, int item, int next_item, char* lds, bf16x8 (&qf)[4], float (&wq)[16]) {
;     ...
; #pragma unroll
;     for (int i = 0; i < 64; ++i) { const int idx = gt + 128 * i; const float v = (idx < n) ? scq[idx] : lo; const float u = (v - lo) * scale; uu[i] = u;
;       if (big && idx < n) { int bb = (int)u; bb = bb > 1023 ? 1023 : bb; atomicAdd(&histq[bb], 1); } }
.Lsel_B_1_part:
	s_sub_i32 s2, s40, 0x400
	ds_read_b32 v8, v181 offset:4096
	ds_read_b32 v9, v181 offset:4608
	ds_read_b32 v10, v181 offset:5120
	ds_read_b32 v11, v181 offset:5632
	ds_read_b32 v12, v181 offset:6144
	ds_read_b32 v13, v181 offset:6656
	ds_read_b32 v14, v181 offset:7168
	ds_read_b32 v15, v181 offset:7680
	v_cmp_gt_i32_e64 s[66:67], s2, v180
	s_sub_i32 s3, s2, 0x80
	v_cmp_gt_i32_e64 s[68:69], s3, v180
	s_sub_i32 s3, s2, 0x100
	v_cmp_gt_i32_e64 s[70:71], s3, v180
	s_sub_i32 s3, s2, 0x180
	v_cmp_gt_i32_e64 s[72:73], s3, v180
	s_sub_i32 s3, s2, 0x200
	v_cmp_gt_i32_e64 s[74:75], s3, v180
	s_sub_i32 s3, s2, 0x280
	v_cmp_gt_i32_e64 s[76:77], s3, v180
	s_sub_i32 s3, s2, 0x300
	v_cmp_gt_i32_e64 s[78:79], s3, v180
	s_sub_i32 s3, s2, 0x380
	v_cmp_gt_i32_e64 s[80:81], s3, v180
	s_waitcnt lgkmcnt(7)
	v_fma_f32 v8, v8, v193, v194
	v_cndmask_b32_e64 v124, 0, v8, s[66:67]
	v_cmp_ge_f32_e32 vcc, v124, v240
	v_lshl_add_u32 v16, v124, 2, s10
	v_cndmask_b32_e64 v16, v205, v16, s[66:67]
	v_cndmask_b32_e32 v16, v241, v16, vcc
	ds_add_u32 v16, v206
	s_waitcnt lgkmcnt(7)
	v_fma_f32 v9, v9, v193, v194
	v_cndmask_b32_e64 v125, 0, v9, s[68:69]
	v_cmp_ge_f32_e32 vcc, v125, v240
	v_lshl_add_u32 v17, v125, 2, s10
	v_cndmask_b32_e64 v17, v205, v17, s[68:69]
	v_cndmask_b32_e32 v17, v241, v17, vcc
	ds_add_u32 v17, v206
	s_waitcnt lgkmcnt(7)
	v_fma_f32 v10, v10, v193, v194
	v_cndmask_b32_e64 v126, 0, v10, s[70:71]
	v_cmp_ge_f32_e32 vcc, v126, v240
	v_lshl_add_u32 v18, v126, 2, s10
	v_cndmask_b32_e64 v18, v205, v18, s[70:71]
	v_cndmask_b32_e32 v18, v241, v18, vcc
	ds_add_u32 v18, v206
	s_waitcnt lgkmcnt(7)
	v_fma_f32 v11, v11, v193, v194
	v_cndmask_b32_e64 v127, 0, v11, s[72:73]
	v_cmp_ge_f32_e32 vcc, v127, v240
	v_lshl_add_u32 v19, v127, 2, s10
	v_cndmask_b32_e64 v19, v205, v19, s[72:73]
	v_cndmask_b32_e32 v19, v241, v19, vcc
	ds_add_u32 v19, v206
	s_waitcnt lgkmcnt(7)
	v_fma_f32 v12, v12, v193, v194
	v_cndmask_b32_e64 v128, 0, v12, s[74:75]
	v_cmp_ge_f32_e32 vcc, v128, v240
	v_lshl_add_u32 v20, v128, 2, s10
	v_cndmask_b32_e64 v20, v205, v20, s[74:75]
	v_cndmask_b32_e32 v20, v241, v20, vcc
	ds_add_u32 v20, v206
	s_waitcnt lgkmcnt(7)
	v_fma_f32 v13, v13, v193, v194
	v_cndmask_b32_e64 v129, 0, v13, s[76:77]
	v_cmp_ge_f32_e32 vcc, v129, v240
	v_lshl_add_u32 v21, v129, 2, s10
	v_cndmask_b32_e64 v21, v205, v21, s[76:77]
	v_cndmask_b32_e32 v21, v241, v21, vcc
	ds_add_u32 v21, v206
	s_waitcnt lgkmcnt(7)
	v_fma_f32 v14, v14, v193, v194
	v_cndmask_b32_e64 v130, 0, v14, s[78:79]
	v_cmp_ge_f32_e32 vcc, v130, v240
	v_lshl_add_u32 v22, v130, 2, s10
	v_cndmask_b32_e64 v22, v205, v22, s[78:79]
	v_cndmask_b32_e32 v22, v241, v22, vcc
	ds_add_u32 v22, v206
	s_waitcnt lgkmcnt(7)
	v_fma_f32 v15, v15, v193, v194
	v_cndmask_b32_e64 v131, 0, v15, s[80:81]
	v_cmp_ge_f32_e32 vcc, v131, v240
	v_lshl_add_u32 v23, v131, 2, s10
	v_cndmask_b32_e64 v23, v205, v23, s[80:81]
	v_cndmask_b32_e32 v23, v241, v23, vcc
	ds_add_u32 v23, v206
	s_branch .Lsel_B_done
.Lsel_B_2_part:
	s_sub_i32 s2, s40, 0x800
	ds_read_b32 v8, v181 offset:8192
	ds_read_b32 v9, v181 offset:8704
	ds_read_b32 v10, v181 offset:9216
	ds_read_b32 v11, v181 offset:9728
	ds_read_b32 v12, v181 offset:10240
	ds_read_b32 v13, v181 offset:10752
	ds_read_b32 v14, v181 offset:11264
	ds_read_b32 v15, v181 offset:11776
	v_cmp_gt_i32_e64 s[66:67], s2, v180
	s_sub_i32 s3, s2, 0x80
	v_cmp_gt_i32_e64 s[68:69], s3, v180
	s_sub_i32 s3, s2, 0x100
	v_cmp_gt_i32_e64 s[70:71], s3, v180
	s_sub_i32 s3, s2, 0x180
	v_cmp_gt_i32_e64 s[72:73], s3, v180
	s_sub_i32 s3, s2, 0x200
	v_cmp_gt_i32_e64 s[74:75], s3, v180
	s_sub_i32 s3, s2, 0x280
	v_cmp_gt_i32_e64 s[76:77], s3, v180
	s_sub_i32 s3, s2, 0x300
	v_cmp_gt_i32_e64 s[78:79], s3, v180
	s_sub_i32 s3, s2, 0x380
	v_cmp_gt_i32_e64 s[80:81], s3, v180
	s_waitcnt lgkmcnt(7)
	v_fma_f32 v8, v8, v193, v194
	v_cndmask_b32_e64 v132, 0, v8, s[66:67]
	v_cmp_ge_f32_e32 vcc, v132, v240
	v_lshl_add_u32 v16, v132, 2, s10
	v_cndmask_b32_e64 v16, v205, v16, s[66:67]
	v_cndmask_b32_e32 v16, v241, v16, vcc
	ds_add_u32 v16, v206
	s_waitcnt lgkmcnt(7)
	v_fma_f32 v9, v9, v193, v194
	v_cndmask_b32_e64 v133, 0, v9, s[68:69]
	v_cmp_ge_f32_e32 vcc, v133, v240
	v_lshl_add_u32 v17, v133, 2, s10
	v_cndmask_b32_e64 v17, v205, v17, s[68:69]
	v_cndmask_b32_e32 v17, v241, v17, vcc
	ds_add_u32 v17, v206
	s_waitcnt lgkmcnt(7)
	v_fma_f32 v10, v10, v193, v194
	v_cndmask_b32_e64 v134, 0, v10, s[70:71]
	v_cmp_ge_f32_e32 vcc, v134, v240
	v_lshl_add_u32 v18, v134, 2, s10
	v_cndmask_b32_e64 v18, v205, v18, s[70:71]
	v_cndmask_b32_e32 v18, v241, v18, vcc
	ds_add_u32 v18, v206
	s_waitcnt lgkmcnt(7)
	v_fma_f32 v11, v11, v193, v194
	v_cndmask_b32_e64 v135, 0, v11, s[72:73]
	v_cmp_ge_f32_e32 vcc, v135, v240
	v_lshl_add_u32 v19, v135, 2, s10
	v_cndmask_b32_e64 v19, v205, v19, s[72:73]
	v_cndmask_b32_e32 v19, v241, v19, vcc
	ds_add_u32 v19, v206
	s_waitcnt lgkmcnt(7)
	v_fma_f32 v12, v12, v193, v194
	v_cndmask_b32_e64 v136, 0, v12, s[74:75]
	v_cmp_ge_f32_e32 vcc, v136, v240
	v_lshl_add_u32 v20, v136, 2, s10
	v_cndmask_b32_e64 v20, v205, v20, s[74:75]
	v_cndmask_b32_e32 v20, v241, v20, vcc
	ds_add_u32 v20, v206
	s_waitcnt lgkmcnt(7)
	v_fma_f32 v13, v13, v193, v194
	v_cndmask_b32_e64 v137, 0, v13, s[76:77]
	v_cmp_ge_f32_e32 vcc, v137, v240
	v_lshl_add_u32 v21, v137, 2, s10
	v_cndmask_b32_e64 v21, v205, v21, s[76:77]
	v_cndmask_b32_e32 v21, v241, v21, vcc
	ds_add_u32 v21, v206
	s_waitcnt lgkmcnt(7)
	v_fma_f32 v14, v14, v193, v194
	v_cndmask_b32_e64 v138, 0, v14, s[78:79]
	v_cmp_ge_f32_e32 vcc, v138, v240
	v_lshl_add_u32 v22, v138, 2, s10
	v_cndmask_b32_e64 v22, v205, v22, s[78:79]
	v_cndmask_b32_e32 v22, v241, v22, vcc
	ds_add_u32 v22, v206
	s_waitcnt lgkmcnt(7)
	v_fma_f32 v15, v15, v193, v194
	v_cndmask_b32_e64 v139, 0, v15, s[80:81]
	v_cmp_ge_f32_e32 vcc, v139, v240
	v_lshl_add_u32 v23, v139, 2, s10
	v_cndmask_b32_e64 v23, v205, v23, s[80:81]
	v_cndmask_b32_e32 v23, v241, v23, vcc
	ds_add_u32 v23, v206
	s_branch .Lsel_B_done
; DI void selectA_item(const Params& p, int item, int next_item, char* lds, bf16x8 (&qf)[4], float (&wq)[16]) {
;     ...
; #pragma unroll
;     for (int i = 0; i < 64; ++i) { const int idx = gt + 128 * i; const float v = (idx < n) ? scq[idx] : lo; const float u = (v - lo) * scale; uu[i] = u;
;       if (big && idx < n) { int bb = (int)u; bb = bb > 1023 ? 1023 : bb; atomicAdd(&histq[bb], 1); } }
.Lsel_B_3_part:
	s_sub_i32 s2, s40, 0xc00
	ds_read_b32 v8, v181 offset:12288
	ds_read_b32 v9, v181 offset:12800
	ds_read_b32 v10, v181 offset:13312
	ds_read_b32 v11, v181 offset:13824
	ds_read_b32 v12, v181 offset:14336
	ds_read_b32 v13, v181 offset:14848
	ds_read_b32 v14, v181 offset:15360
	ds_read_b32 v15, v181 offset:15872
	v_cmp_gt_i32_e64 s[66:67], s2, v180
	s_sub_i32 s3, s2, 0x80
	v_cmp_gt_i32_e64 s[68:69], s3, v180
	s_sub_i32 s3, s2, 0x100
	v_cmp_gt_i32_e64 s[70:71], s3, v180
	s_sub_i32 s3, s2, 0x180
	v_cmp_gt_i32_e64 s[72:73], s3, v180
	s_sub_i32 s3, s2, 0x200
	v_cmp_gt_i32_e64 s[74:75], s3, v180
	s_sub_i32 s3, s2, 0x280
	v_cmp_gt_i32_e64 s[76:77], s3, v180
	s_sub_i32 s3, s2, 0x300
	v_cmp_gt_i32_e64 s[78:79], s3, v180
	s_sub_i32 s3, s2, 0x380
	v_cmp_gt_i32_e64 s[80:81], s3, v180
	s_waitcnt lgkmcnt(7)
	v_fma_f32 v8, v8, v193, v194
	v_cndmask_b32_e64 v140, 0, v8, s[66:67]
	v_cmp_ge_f32_e32 vcc, v140, v240
	v_lshl_add_u32 v16, v140, 2, s10
	v_cndmask_b32_e64 v16, v205, v16, s[66:67]
	v_cndmask_b32_e32 v16, v241, v16, vcc
	ds_add_u32 v16, v206
	s_waitcnt lgkmcnt(7)
	v_fma_f32 v9, v9, v193, v194
	v_cndmask_b32_e64 v141, 0, v9, s[68:69]
	v_cmp_ge_f32_e32 vcc, v141, v240
	v_lshl_add_u32 v17, v141, 2, s10
	v_cndmask_b32_e64 v17, v205, v17, s[68:69]
	v_cndmask_b32_e32 v17, v241, v17, vcc
	ds_add_u32 v17, v206
	s_waitcnt lgkmcnt(7)
	v_fma_f32 v10, v10, v193, v194
	v_cndmask_b32_e64 v142, 0, v10, s[70:71]
	v_cmp_ge_f32_e32 vcc, v142, v240
	v_lshl_add_u32 v18, v142, 2, s10
	v_cndmask_b32_e64 v18, v205, v18, s[70:71]
	v_cndmask_b32_e32 v18, v241, v18, vcc
	ds_add_u32 v18, v206
	s_waitcnt lgkmcnt(7)
	v_fma_f32 v11, v11, v193, v194
	v_cndmask_b32_e64 v143, 0, v11, s[72:73]
	v_cmp_ge_f32_e32 vcc, v143, v240
	v_lshl_add_u32 v19, v143, 2, s10
	v_cndmask_b32_e64 v19, v205, v19, s[72:73]
	v_cndmask_b32_e32 v19, v241, v19, vcc
	ds_add_u32 v19, v206
	s_waitcnt lgkmcnt(7)
	v_fma_f32 v12, v12, v193, v194
	v_cndmask_b32_e64 v144, 0, v12, s[74:75]
	v_cmp_ge_f32_e32 vcc, v144, v240
	v_lshl_add_u32 v20, v144, 2, s10
	v_cndmask_b32_e64 v20, v205, v20, s[74:75]
	v_cndmask_b32_e32 v20, v241, v20, vcc
	ds_add_u32 v20, v206
	s_waitcnt lgkmcnt(7)
	v_fma_f32 v13, v13, v193, v194
	v_cndmask_b32_e64 v145, 0, v13, s[76:77]
	v_cmp_ge_f32_e32 vcc, v145, v240
	v_lshl_add_u32 v21, v145, 2, s10
	v_cndmask_b32_e64 v21, v205, v21, s[76:77]
	v_cndmask_b32_e32 v21, v241, v21, vcc
	ds_add_u32 v21, v206
	s_waitcnt lgkmcnt(7)
	v_fma_f32 v14, v14, v193, v194
	v_cndmask_b32_e64 v146, 0, v14, s[78:79]
	v_cmp_ge_f32_e32 vcc, v146, v240
	v_lshl_add_u32 v22, v146, 2, s10
	v_cndmask_b32_e64 v22, v205, v22, s[78:79]
	v_cndmask_b32_e32 v22, v241, v22, vcc
	ds_add_u32 v22, v206
	s_waitcnt lgkmcnt(7)
	v_fma_f32 v15, v15, v193, v194
	v_cndmask_b32_e64 v147, 0, v15, s[80:81]
	v_cmp_ge_f32_e32 vcc, v147, v240
	v_lshl_add_u32 v23, v147, 2, s10
	v_cndmask_b32_e64 v23, v205, v23, s[80:81]
	v_cndmask_b32_e32 v23, v241, v23, vcc
	ds_add_u32 v23, v206
	s_branch .Lsel_B_done
.Lsel_B_4_part:
	s_sub_i32 s2, s40, 0x1000
	ds_read_b32 v8, v181 offset:16384
	ds_read_b32 v9, v181 offset:16896
	ds_read_b32 v10, v181 offset:17408
	ds_read_b32 v11, v181 offset:17920
	ds_read_b32 v12, v181 offset:18432
	ds_read_b32 v13, v181 offset:18944
	ds_read_b32 v14, v181 offset:19456
	ds_read_b32 v15, v181 offset:19968
	v_cmp_gt_i32_e64 s[66:67], s2, v180
	s_sub_i32 s3, s2, 0x80
	v_cmp_gt_i32_e64 s[68:69], s3, v180
	s_sub_i32 s3, s2, 0x100
	v_cmp_gt_i32_e64 s[70:71], s3, v180
	s_sub_i32 s3, s2, 0x180
	v_cmp_gt_i32_e64 s[72:73], s3, v180
	s_sub_i32 s3, s2, 0x200
	v_cmp_gt_i32_e64 s[74:75], s3, v180
	s_sub_i32 s3, s2, 0x280
	v_cmp_gt_i32_e64 s[76:77], s3, v180
	s_sub_i32 s3, s2, 0x300
	v_cmp_gt_i32_e64 s[78:79], s3, v180
	s_sub_i32 s3, s2, 0x380
	v_cmp_gt_i32_e64 s[80:81], s3, v180
	s_waitcnt lgkmcnt(7)
	v_fma_f32 v8, v8, v193, v194
	v_cndmask_b32_e64 v148, 0, v8, s[66:67]
	v_cmp_ge_f32_e32 vcc, v148, v240
	v_lshl_add_u32 v16, v148, 2, s10
	v_cndmask_b32_e64 v16, v205, v16, s[66:67]
	v_cndmask_b32_e32 v16, v241, v16, vcc
	ds_add_u32 v16, v206
	s_waitcnt lgkmcnt(7)
	v_fma_f32 v9, v9, v193, v194
	v_cndmask_b32_e64 v149, 0, v9, s[68:69]
	v_cmp_ge_f32_e32 vcc, v149, v240
	v_lshl_add_u32 v17, v149, 2, s10
	v_cndmask_b32_e64 v17, v205, v17, s[68:69]
	v_cndmask_b32_e32 v17, v241, v17, vcc
	ds_add_u32 v17, v206
	s_waitcnt lgkmcnt(7)
	v_fma_f32 v10, v10, v193, v194
	v_cndmask_b32_e64 v150, 0, v10, s[70:71]
	v_cmp_ge_f32_e32 vcc, v150, v240
	v_lshl_add_u32 v18, v150, 2, s10
	v_cndmask_b32_e64 v18, v205, v18, s[70:71]
	v_cndmask_b32_e32 v18, v241, v18, vcc
	ds_add_u32 v18, v206
	s_waitcnt lgkmcnt(7)
	v_fma_f32 v11, v11, v193, v194
	v_cndmask_b32_e64 v151, 0, v11, s[72:73]
	v_cmp_ge_f32_e32 vcc, v151, v240
	v_lshl_add_u32 v19, v151, 2, s10
	v_cndmask_b32_e64 v19, v205, v19, s[72:73]
	v_cndmask_b32_e32 v19, v241, v19, vcc
	ds_add_u32 v19, v206
	s_waitcnt lgkmcnt(7)
	v_fma_f32 v12, v12, v193, v194
	v_cndmask_b32_e64 v152, 0, v12, s[74:75]
	v_cmp_ge_f32_e32 vcc, v152, v240
	v_lshl_add_u32 v20, v152, 2, s10
	v_cndmask_b32_e64 v20, v205, v20, s[74:75]
	v_cndmask_b32_e32 v20, v241, v20, vcc
	ds_add_u32 v20, v206
	s_waitcnt lgkmcnt(7)
	v_fma_f32 v13, v13, v193, v194
	v_cndmask_b32_e64 v153, 0, v13, s[76:77]
	v_cmp_ge_f32_e32 vcc, v153, v240
	v_lshl_add_u32 v21, v153, 2, s10
	v_cndmask_b32_e64 v21, v205, v21, s[76:77]
	v_cndmask_b32_e32 v21, v241, v21, vcc
	ds_add_u32 v21, v206
	s_waitcnt lgkmcnt(7)
	v_fma_f32 v14, v14, v193, v194
	v_cndmask_b32_e64 v154, 0, v14, s[78:79]
	v_cmp_ge_f32_e32 vcc, v154, v240
	v_lshl_add_u32 v22, v154, 2, s10
	v_cndmask_b32_e64 v22, v205, v22, s[78:79]
	v_cndmask_b32_e32 v22, v241, v22, vcc
	ds_add_u32 v22, v206
	s_waitcnt lgkmcnt(7)
	v_fma_f32 v15, v15, v193, v194
	v_cndmask_b32_e64 v155, 0, v15, s[80:81]
	v_cmp_ge_f32_e32 vcc, v155, v240
	v_lshl_add_u32 v23, v155, 2, s10
	v_cndmask_b32_e64 v23, v205, v23, s[80:81]
	v_cndmask_b32_e32 v23, v241, v23, vcc
	ds_add_u32 v23, v206
	s_branch .Lsel_B_done
; DI void selectA_item(const Params& p, int item, int next_item, char* lds, bf16x8 (&qf)[4], float (&wq)[16]) {
;     ...
; #pragma unroll
;     for (int i = 0; i < 64; ++i) { const int idx = gt + 128 * i; const float v = (idx < n) ? scq[idx] : lo; const float u = (v - lo) * scale; uu[i] = u;
;       if (big && idx < n) { int bb = (int)u; bb = bb > 1023 ? 1023 : bb; atomicAdd(&histq[bb], 1); } }
.Lsel_B_5_part:
	s_sub_i32 s2, s40, 0x1400
	ds_read_b32 v8, v181 offset:20480
	ds_read_b32 v9, v181 offset:20992
	ds_read_b32 v10, v181 offset:21504
	ds_read_b32 v11, v181 offset:22016
	ds_read_b32 v12, v181 offset:22528
	ds_read_b32 v13, v181 offset:23040
	ds_read_b32 v14, v181 offset:23552
	ds_read_b32 v15, v181 offset:24064
	v_cmp_gt_i32_e64 s[66:67], s2, v180
	s_sub_i32 s3, s2, 0x80
	v_cmp_gt_i32_e64 s[68:69], s3, v180
	s_sub_i32 s3, s2, 0x100
	v_cmp_gt_i32_e64 s[70:71], s3, v180
	s_sub_i32 s3, s2, 0x180
	v_cmp_gt_i32_e64 s[72:73], s3, v180
	s_sub_i32 s3, s2, 0x200
	v_cmp_gt_i32_e64 s[74:75], s3, v180
	s_sub_i32 s3, s2, 0x280
	v_cmp_gt_i32_e64 s[76:77], s3, v180
	s_sub_i32 s3, s2, 0x300
	v_cmp_gt_i32_e64 s[78:79], s3, v180
	s_sub_i32 s3, s2, 0x380
	v_cmp_gt_i32_e64 s[80:81], s3, v180
	s_waitcnt lgkmcnt(7)
	v_fma_f32 v8, v8, v193, v194
	v_cndmask_b32_e64 v156, 0, v8, s[66:67]
	v_cmp_ge_f32_e32 vcc, v156, v240
	v_lshl_add_u32 v16, v156, 2, s10
	v_cndmask_b32_e64 v16, v205, v16, s[66:67]
	v_cndmask_b32_e32 v16, v241, v16, vcc
	ds_add_u32 v16, v206
	s_waitcnt lgkmcnt(7)
	v_fma_f32 v9, v9, v193, v194
	v_cndmask_b32_e64 v157, 0, v9, s[68:69]
	v_cmp_ge_f32_e32 vcc, v157, v240
	v_lshl_add_u32 v17, v157, 2, s10
	v_cndmask_b32_e64 v17, v205, v17, s[68:69]
	v_cndmask_b32_e32 v17, v241, v17, vcc
	ds_add_u32 v17, v206
	s_waitcnt lgkmcnt(7)
	v_fma_f32 v10, v10, v193, v194
	v_cndmask_b32_e64 v158, 0, v10, s[70:71]
	v_cmp_ge_f32_e32 vcc, v158, v240
	v_lshl_add_u32 v18, v158, 2, s10
	v_cndmask_b32_e64 v18, v205, v18, s[70:71]
	v_cndmask_b32_e32 v18, v241, v18, vcc
	ds_add_u32 v18, v206
	s_waitcnt lgkmcnt(7)
	v_fma_f32 v11, v11, v193, v194
	v_cndmask_b32_e64 v159, 0, v11, s[72:73]
	v_cmp_ge_f32_e32 vcc, v159, v240
	v_lshl_add_u32 v19, v159, 2, s10
	v_cndmask_b32_e64 v19, v205, v19, s[72:73]
	v_cndmask_b32_e32 v19, v241, v19, vcc
	ds_add_u32 v19, v206
	s_waitcnt lgkmcnt(7)
	v_fma_f32 v12, v12, v193, v194
	v_cndmask_b32_e64 v160, 0, v12, s[74:75]
	v_cmp_ge_f32_e32 vcc, v160, v240
	v_lshl_add_u32 v20, v160, 2, s10
	v_cndmask_b32_e64 v20, v205, v20, s[74:75]
	v_cndmask_b32_e32 v20, v241, v20, vcc
	ds_add_u32 v20, v206
	s_waitcnt lgkmcnt(7)
	v_fma_f32 v13, v13, v193, v194
	v_cndmask_b32_e64 v161, 0, v13, s[76:77]
	v_cmp_ge_f32_e32 vcc, v161, v240
	v_lshl_add_u32 v21, v161, 2, s10
	v_cndmask_b32_e64 v21, v205, v21, s[76:77]
	v_cndmask_b32_e32 v21, v241, v21, vcc
	ds_add_u32 v21, v206
	s_waitcnt lgkmcnt(7)
	v_fma_f32 v14, v14, v193, v194
	v_cndmask_b32_e64 v162, 0, v14, s[78:79]
	v_cmp_ge_f32_e32 vcc, v162, v240
	v_lshl_add_u32 v22, v162, 2, s10
	v_cndmask_b32_e64 v22, v205, v22, s[78:79]
	v_cndmask_b32_e32 v22, v241, v22, vcc
	ds_add_u32 v22, v206
	s_waitcnt lgkmcnt(7)
	v_fma_f32 v15, v15, v193, v194
	v_cndmask_b32_e64 v163, 0, v15, s[80:81]
	v_cmp_ge_f32_e32 vcc, v163, v240
	v_lshl_add_u32 v23, v163, 2, s10
	v_cndmask_b32_e64 v23, v205, v23, s[80:81]
	v_cndmask_b32_e32 v23, v241, v23, vcc
	ds_add_u32 v23, v206
	s_branch .Lsel_B_done
.Lsel_B_6_part:
	s_sub_i32 s2, s40, 0x1800
	ds_read_b32 v8, v181 offset:24576
	ds_read_b32 v9, v181 offset:25088
	ds_read_b32 v10, v181 offset:25600
	ds_read_b32 v11, v181 offset:26112
	ds_read_b32 v12, v181 offset:26624
	ds_read_b32 v13, v181 offset:27136
	ds_read_b32 v14, v181 offset:27648
	ds_read_b32 v15, v181 offset:28160
	v_cmp_gt_i32_e64 s[66:67], s2, v180
	s_sub_i32 s3, s2, 0x80
	v_cmp_gt_i32_e64 s[68:69], s3, v180
	s_sub_i32 s3, s2, 0x100
	v_cmp_gt_i32_e64 s[70:71], s3, v180
	s_sub_i32 s3, s2, 0x180
	v_cmp_gt_i32_e64 s[72:73], s3, v180
	s_sub_i32 s3, s2, 0x200
	v_cmp_gt_i32_e64 s[74:75], s3, v180
	s_sub_i32 s3, s2, 0x280
	v_cmp_gt_i32_e64 s[76:77], s3, v180
	s_sub_i32 s3, s2, 0x300
	v_cmp_gt_i32_e64 s[78:79], s3, v180
	s_sub_i32 s3, s2, 0x380
	v_cmp_gt_i32_e64 s[80:81], s3, v180
	s_waitcnt lgkmcnt(7)
	v_fma_f32 v8, v8, v193, v194
	v_cndmask_b32_e64 v164, 0, v8, s[66:67]
	v_cmp_ge_f32_e32 vcc, v164, v240
	v_lshl_add_u32 v16, v164, 2, s10
	v_cndmask_b32_e64 v16, v205, v16, s[66:67]
	v_cndmask_b32_e32 v16, v241, v16, vcc
	ds_add_u32 v16, v206
	s_waitcnt lgkmcnt(7)
	v_fma_f32 v9, v9, v193, v194
	v_cndmask_b32_e64 v165, 0, v9, s[68:69]
	v_cmp_ge_f32_e32 vcc, v165, v240
	v_lshl_add_u32 v17, v165, 2, s10
	v_cndmask_b32_e64 v17, v205, v17, s[68:69]
	v_cndmask_b32_e32 v17, v241, v17, vcc
	ds_add_u32 v17, v206
	s_waitcnt lgkmcnt(7)
	v_fma_f32 v10, v10, v193, v194
	v_cndmask_b32_e64 v166, 0, v10, s[70:71]
	v_cmp_ge_f32_e32 vcc, v166, v240
	v_lshl_add_u32 v18, v166, 2, s10
	v_cndmask_b32_e64 v18, v205, v18, s[70:71]
	v_cndmask_b32_e32 v18, v241, v18, vcc
	ds_add_u32 v18, v206
	s_waitcnt lgkmcnt(7)
	v_fma_f32 v11, v11, v193, v194
	v_cndmask_b32_e64 v167, 0, v11, s[72:73]
	v_cmp_ge_f32_e32 vcc, v167, v240
	v_lshl_add_u32 v19, v167, 2, s10
	v_cndmask_b32_e64 v19, v205, v19, s[72:73]
	v_cndmask_b32_e32 v19, v241, v19, vcc
	ds_add_u32 v19, v206
	s_waitcnt lgkmcnt(7)
	v_fma_f32 v12, v12, v193, v194
	v_cndmask_b32_e64 v168, 0, v12, s[74:75]
	v_cmp_ge_f32_e32 vcc, v168, v240
	v_lshl_add_u32 v20, v168, 2, s10
	v_cndmask_b32_e64 v20, v205, v20, s[74:75]
	v_cndmask_b32_e32 v20, v241, v20, vcc
	ds_add_u32 v20, v206
	s_waitcnt lgkmcnt(7)
	v_fma_f32 v13, v13, v193, v194
	v_cndmask_b32_e64 v169, 0, v13, s[76:77]
	v_cmp_ge_f32_e32 vcc, v169, v240
	v_lshl_add_u32 v21, v169, 2, s10
	v_cndmask_b32_e64 v21, v205, v21, s[76:77]
	v_cndmask_b32_e32 v21, v241, v21, vcc
	ds_add_u32 v21, v206
	s_waitcnt lgkmcnt(7)
	v_fma_f32 v14, v14, v193, v194
	v_cndmask_b32_e64 v170, 0, v14, s[78:79]
	v_cmp_ge_f32_e32 vcc, v170, v240
	v_lshl_add_u32 v22, v170, 2, s10
	v_cndmask_b32_e64 v22, v205, v22, s[78:79]
	v_cndmask_b32_e32 v22, v241, v22, vcc
	ds_add_u32 v22, v206
	s_waitcnt lgkmcnt(7)
	v_fma_f32 v15, v15, v193, v194
	v_cndmask_b32_e64 v171, 0, v15, s[80:81]
	v_cmp_ge_f32_e32 vcc, v171, v240
	v_lshl_add_u32 v23, v171, 2, s10
	v_cndmask_b32_e64 v23, v205, v23, s[80:81]
	v_cndmask_b32_e32 v23, v241, v23, vcc
	ds_add_u32 v23, v206
	s_branch .Lsel_B_done
; DI void selectA_item(const Params& p, int item, int next_item, char* lds, bf16x8 (&qf)[4], float (&wq)[16]) {
;     ...
; #pragma unroll
;     for (int i = 0; i < 64; ++i) { const int idx = gt + 128 * i; const float v = (idx < n) ? scq[idx] : lo; const float u = (v - lo) * scale; uu[i] = u;
;       if (big && idx < n) { int bb = (int)u; bb = bb > 1023 ? 1023 : bb; atomicAdd(&histq[bb], 1); } }
.Lsel_B_7_part:
	s_sub_i32 s2, s40, 0x1c00
	ds_read_b32 v8, v181 offset:28672
	ds_read_b32 v9, v181 offset:29184
	ds_read_b32 v10, v181 offset:29696
	ds_read_b32 v11, v181 offset:30208
	ds_read_b32 v12, v181 offset:30720
	ds_read_b32 v13, v181 offset:31232
	ds_read_b32 v14, v181 offset:31744
	ds_read_b32 v15, v181 offset:32256
	v_cmp_gt_i32_e64 s[66:67], s2, v180
	s_sub_i32 s3, s2, 0x80
	v_cmp_gt_i32_e64 s[68:69], s3, v180
	s_sub_i32 s3, s2, 0x100
	v_cmp_gt_i32_e64 s[70:71], s3, v180
	s_sub_i32 s3, s2, 0x180
	v_cmp_gt_i32_e64 s[72:73], s3, v180
	s_sub_i32 s3, s2, 0x200
	v_cmp_gt_i32_e64 s[74:75], s3, v180
	s_sub_i32 s3, s2, 0x280
	v_cmp_gt_i32_e64 s[76:77], s3, v180
	s_sub_i32 s3, s2, 0x300
	v_cmp_gt_i32_e64 s[78:79], s3, v180
	s_sub_i32 s3, s2, 0x380
	v_cmp_gt_i32_e64 s[80:81], s3, v180
	s_waitcnt lgkmcnt(7)
	v_fma_f32 v8, v8, v193, v194
	v_cndmask_b32_e64 v172, 0, v8, s[66:67]
	v_cmp_ge_f32_e32 vcc, v172, v240
	v_lshl_add_u32 v16, v172, 2, s10
	v_cndmask_b32_e64 v16, v205, v16, s[66:67]
	v_cndmask_b32_e32 v16, v241, v16, vcc
	ds_add_u32 v16, v206
	s_waitcnt lgkmcnt(7)
	v_fma_f32 v9, v9, v193, v194
	v_cndmask_b32_e64 v173, 0, v9, s[68:69]
	v_cmp_ge_f32_e32 vcc, v173, v240
	v_lshl_add_u32 v17, v173, 2, s10
	v_cndmask_b32_e64 v17, v205, v17, s[68:69]
	v_cndmask_b32_e32 v17, v241, v17, vcc
	ds_add_u32 v17, v206
	s_waitcnt lgkmcnt(7)
	v_fma_f32 v10, v10, v193, v194
	v_cndmask_b32_e64 v174, 0, v10, s[70:71]
	v_cmp_ge_f32_e32 vcc, v174, v240
	v_lshl_add_u32 v18, v174, 2, s10
	v_cndmask_b32_e64 v18, v205, v18, s[70:71]
	v_cndmask_b32_e32 v18, v241, v18, vcc
	ds_add_u32 v18, v206
	s_waitcnt lgkmcnt(7)
	v_fma_f32 v11, v11, v193, v194
	v_cndmask_b32_e64 v175, 0, v11, s[72:73]
	v_cmp_ge_f32_e32 vcc, v175, v240
	v_lshl_add_u32 v19, v175, 2, s10
	v_cndmask_b32_e64 v19, v205, v19, s[72:73]
	v_cndmask_b32_e32 v19, v241, v19, vcc
	ds_add_u32 v19, v206
	s_waitcnt lgkmcnt(7)
	v_fma_f32 v12, v12, v193, v194
	v_cndmask_b32_e64 v176, 0, v12, s[74:75]
	v_cmp_ge_f32_e32 vcc, v176, v240
	v_lshl_add_u32 v20, v176, 2, s10
	v_cndmask_b32_e64 v20, v205, v20, s[74:75]
	v_cndmask_b32_e32 v20, v241, v20, vcc
	ds_add_u32 v20, v206
	s_waitcnt lgkmcnt(7)
	v_fma_f32 v13, v13, v193, v194
	v_cndmask_b32_e64 v177, 0, v13, s[76:77]
	v_cmp_ge_f32_e32 vcc, v177, v240
	v_lshl_add_u32 v21, v177, 2, s10
	v_cndmask_b32_e64 v21, v205, v21, s[76:77]
	v_cndmask_b32_e32 v21, v241, v21, vcc
	ds_add_u32 v21, v206
	s_waitcnt lgkmcnt(7)
	v_fma_f32 v14, v14, v193, v194
	v_cndmask_b32_e64 v178, 0, v14, s[78:79]
	v_cmp_ge_f32_e32 vcc, v178, v240
	v_lshl_add_u32 v22, v178, 2, s10
	v_cndmask_b32_e64 v22, v205, v22, s[78:79]
	v_cndmask_b32_e32 v22, v241, v22, vcc
	ds_add_u32 v22, v206
	s_waitcnt lgkmcnt(7)
	v_fma_f32 v15, v15, v193, v194
	v_cndmask_b32_e64 v179, 0, v15, s[80:81]
	v_cmp_ge_f32_e32 vcc, v179, v240
	v_lshl_add_u32 v23, v179, 2, s10
	v_cndmask_b32_e64 v23, v205, v23, s[80:81]
	v_cndmask_b32_e32 v23, v241, v23, vcc
	ds_add_u32 v23, v206
; DI void lds_barrier() { asm volatile("s_waitcnt lgkmcnt(0)" ::: "memory"); __builtin_amdgcn_s_barrier(); asm volatile("" ::: "memory"); }
; DI void selectA_item(const Params& p, int item, int next_item, char* lds, bf16x8 (&qf)[4], float (&wq)[16]) {
;     ...
;     lds_barrier();
;     typedef int i32x4 __attribute__((ext_vector_type(4)));
;     const i32x4 h0 = *(const i32x4*)(histq + gt * 8), h1 = *(const i32x4*)(histq + gt * 8 + 4);
;     const int hh[8] = {h0.x, h0.y, h0.z, h0.w, h1.x, h1.y, h1.z, h1.w};
;     int tot = 0;
; #pragma unroll
;     for (int k = 0; k < 8; ++k) tot += hh[k];
;     int inc = tot;
; #pragma unroll
;     for (int o = 1; o < 64; o <<= 1) { const int ux = __shfl_down(inc, o); if (lane + o < 64) inc += ux; }
;     if (lane == 0) misc[wid] = inc;
;     lds_barrier();
;     {
;       int above = inc - tot + (upper ? 0 : misc[wid + 1]);
;       if (big) {
; #pragma unroll
;         for (int k = 7; k >= 0; --k) { const int c = hh[k]; if (above < 256 && above + c >= 256) { mq[1] = gt * 8 + k; mq[2] = 256 - above; mq[3] = c; } above += c; }
;       }
;     }
;     lds_barrier();
;     const int bstar = mq[1], need = mq[2], cnt = mq[3];
;     const float flo = (float)bstar, fhi = (bstar >= 1023) ? INFINITY : (float)(bstar + 1);
.Lsel_B_done:
	s_waitcnt lgkmcnt(0)
	s_barrier
	s_cmp_lg_u32 s65, 0
	s_cbranch_scc1 .Lsel_D_skip
	v_sub_u32_e32 v0, 63, v183
	v_lshl_add_u32 v0, v0, 6, s41
	ds_read_b128 v[8:11], v0
	ds_read_b128 v[12:15], v0 offset:16
	ds_read_b128 v[16:19], v0 offset:32
	ds_read_b128 v[20:23], v0 offset:48
	s_waitcnt lgkmcnt(0)
	v_add3_u32 v24, v8, v9, v10
	v_add3_u32 v24, v24, v11, v12
	v_add3_u32 v24, v24, v13, v14
	v_add3_u32 v24, v24, v15, v16
	v_add3_u32 v24, v24, v17, v18
	v_add3_u32 v24, v24, v19, v20
	v_add3_u32 v24, v24, v21, v22
	v_add_u32_e32 v24, v24, v23
	v_mov_b32_e32 v25, v24
	s_nop 1
	v_add_u32_dpp v25, v25, v25 row_shr:1 row_mask:0xf bank_mask:0xf
	s_nop 1
	v_add_u32_dpp v25, v25, v25 row_shr:2 row_mask:0xf bank_mask:0xf
	s_nop 1
	v_add_u32_dpp v25, v25, v25 row_shr:4 row_mask:0xf bank_mask:0xf
	s_nop 1
	v_add_u32_dpp v25, v25, v25 row_shr:8 row_mask:0xf bank_mask:0xf
	s_nop 1
	v_add_u32_dpp v25, v25, v25 row_bcast:15 row_mask:0xa bank_mask:0xf
	s_nop 1
	v_add_u32_dpp v25, v25, v25 row_bcast:31 row_mask:0xc bank_mask:0xf
	s_nop 1
	v_sub_u32_e32 v26, v25, v24
	v_sub_u32_e32 v27, 0x100, v26
	v_mov_b32_e32 v30, -1
	v_mov_b32_e32 v31, 0
	v_mov_b32_e32 v50, 0
	v_add_u32_e32 v29, -1, v27
	v_cmp_lt_u32_e64 s[46:47], v29, v23
	v_sub_u32_e32 v28, v27, v23
	s_nop 0
	v_cndmask_b32_e64 v30, v30, 15, s[46:47]
	v_cndmask_b32_e64 v31, v31, v27, s[46:47]
	v_cndmask_b32_e64 v50, v50, v23, s[46:47]
	v_add_u32_e32 v29, -1, v28
	v_cmp_lt_u32_e64 s[48:49], v29, v22
	v_sub_u32_e32 v27, v28, v22
	s_nop 0
	v_cndmask_b32_e64 v30, v30, 14, s[48:49]
	v_cndmask_b32_e64 v31, v31, v28, s[48:49]
	v_cndmask_b32_e64 v50, v50, v22, s[48:49]
	v_add_u32_e32 v29, -1, v27
	v_cmp_lt_u32_e64 s[46:47], v29, v21
	v_sub_u32_e32 v28, v27, v21
	s_nop 0
	v_cndmask_b32_e64 v30, v30, 13, s[46:47]
	v_cndmask_b32_e64 v31, v31, v27, s[46:47]
	v_cndmask_b32_e64 v50, v50, v21, s[46:47]
	v_add_u32_e32 v29, -1, v28
	v_cmp_lt_u32_e64 s[48:49], v29, v20
	v_sub_u32_e32 v27, v28, v20
	s_nop 0
	v_cndmask_b32_e64 v30, v30, 12, s[48:49]
	v_cndmask_b32_e64 v31, v31, v28, s[48:49]
	v_cndmask_b32_e64 v50, v50, v20, s[48:49]
	v_add_u32_e32 v29, -1, v27
	v_cmp_lt_u32_e64 s[46:47], v29, v19
	v_sub_u32_e32 v28, v27, v19
	s_nop 0
	v_cndmask_b32_e64 v30, v30, 11, s[46:47]
	v_cndmask_b32_e64 v31, v31, v27, s[46:47]
	v_cndmask_b32_e64 v50, v50, v19, s[46:47]
	v_add_u32_e32 v29, -1, v28
	v_cmp_lt_u32_e64 s[48:49], v29, v18
	v_sub_u32_e32 v27, v28, v18
	s_nop 0
	v_cndmask_b32_e64 v30, v30, 10, s[48:49]
	v_cndmask_b32_e64 v31, v31, v28, s[48:49]
	v_cndmask_b32_e64 v50, v50, v18, s[48:49]
	v_add_u32_e32 v29, -1, v27
	v_cmp_lt_u32_e64 s[46:47], v29, v17
	v_sub_u32_e32 v28, v27, v17
	s_nop 0
	v_cndmask_b32_e64 v30, v30, 9, s[46:47]
	v_cndmask_b32_e64 v31, v31, v27, s[46:47]
	v_cndmask_b32_e64 v50, v50, v17, s[46:47]
	v_add_u32_e32 v29, -1, v28
	v_cmp_lt_u32_e64 s[48:49], v29, v16
	v_sub_u32_e32 v27, v28, v16
	s_nop 0
	v_cndmask_b32_e64 v30, v30, 8, s[48:49]
	v_cndmask_b32_e64 v31, v31, v28, s[48:49]
	v_cndmask_b32_e64 v50, v50, v16, s[48:49]
	v_add_u32_e32 v29, -1, v27
	v_cmp_lt_u32_e64 s[46:47], v29, v15
	v_sub_u32_e32 v28, v27, v15
	s_nop 0
	v_cndmask_b32_e64 v30, v30, 7, s[46:47]
	v_cndmask_b32_e64 v31, v31, v27, s[46:47]
	v_cndmask_b32_e64 v50, v50, v15, s[46:47]
	v_add_u32_e32 v29, -1, v28
	v_cmp_lt_u32_e64 s[48:49], v29, v14
	v_sub_u32_e32 v27, v28, v14
	s_nop 0
	v_cndmask_b32_e64 v30, v30, 6, s[48:49]
	v_cndmask_b32_e64 v31, v31, v28, s[48:49]
	v_cndmask_b32_e64 v50, v50, v14, s[48:49]
	v_add_u32_e32 v29, -1, v27
	v_cmp_lt_u32_e64 s[46:47], v29, v13
	v_sub_u32_e32 v28, v27, v13
	s_nop 0
	v_cndmask_b32_e64 v30, v30, 5, s[46:47]
	v_cndmask_b32_e64 v31, v31, v27, s[46:47]
	v_cndmask_b32_e64 v50, v50, v13, s[46:47]
	v_add_u32_e32 v29, -1, v28
	v_cmp_lt_u32_e64 s[48:49], v29, v12
	v_sub_u32_e32 v27, v28, v12
	s_nop 0
	v_cndmask_b32_e64 v30, v30, 4, s[48:49]
	v_cndmask_b32_e64 v31, v31, v28, s[48:49]
	v_cndmask_b32_e64 v50, v50, v12, s[48:49]
	v_add_u32_e32 v29, -1, v27
	v_cmp_lt_u32_e64 s[46:47], v29, v11
	v_sub_u32_e32 v28, v27, v11
	s_nop 0
	v_cndmask_b32_e64 v30, v30, 3, s[46:47]
	v_cndmask_b32_e64 v31, v31, v27, s[46:47]
	v_cndmask_b32_e64 v50, v50, v11, s[46:47]
	v_add_u32_e32 v29, -1, v28
	v_cmp_lt_u32_e64 s[48:49], v29, v10
	v_sub_u32_e32 v27, v28, v10
	s_nop 0
	v_cndmask_b32_e64 v30, v30, 2, s[48:49]
	v_cndmask_b32_e64 v31, v31, v28, s[48:49]
	v_cndmask_b32_e64 v50, v50, v10, s[48:49]
	v_add_u32_e32 v29, -1, v27
	v_cmp_lt_u32_e64 s[46:47], v29, v9
	v_sub_u32_e32 v28, v27, v9
	s_nop 0
	v_cndmask_b32_e64 v30, v30, 1, s[46:47]
	v_cndmask_b32_e64 v31, v31, v27, s[46:47]
	v_cndmask_b32_e64 v50, v50, v9, s[46:47]
	v_add_u32_e32 v29, -1, v28
	v_cmp_lt_u32_e64 s[48:49], v29, v8
	v_sub_u32_e32 v27, v28, v8
	s_nop 0
	v_cndmask_b32_e64 v30, v30, 0, s[48:49]
	v_cndmask_b32_e64 v31, v31, v28, s[48:49]
	v_cndmask_b32_e64 v50, v50, v8, s[48:49]
	v_cmp_le_i32_e32 vcc, 0, v30
	s_nop 3
	s_cmp_eq_u64 vcc, 0
	s_cbranch_scc1 .Lsel_fallback
	s_ff1_i32_b64 s64, vcc
	s_nop 0
	v_readlane_b32 s58, v30, s64
	v_readlane_b32 s59, v31, s64
	v_readlane_b32 s60, v50, s64
	s_sub_i32 s2, 63, s64
	s_lshl_b32 s2, s2, 4
	s_add_i32 s58, s58, s2
	s_cmp_gt_u32 s60, 0x80
	s_cbranch_scc1 .Lsel_fallback
	s_sub_i32 s61, 0x100, s59
	v_cvt_f32_i32_e32 v194, s58
	s_add_i32 s2, s58, 1
	v_cvt_f32_i32_e32 v195, s2
	v_add_f32_e32 v194, 0x4b000000, v194
	v_add_f32_e32 v195, 0x4b000000, v195
	s_cmp_ge_u32 s58, 0x3ff
	s_cbranch_scc0 .Lsel_fhi_ok
	v_mov_b32_e32 v195, 0x7f800000

; DI unsigned long long mkcmp(float v, int idx) { return ((unsigned long long)f2ord(v) << 16) | ((unsigned long long)(8191 - idx) << 3); }
; DI void selectA_item(const Params& p, int item, int next_item, char* lds, bf16x8 (&qf)[4], float (&wq)[16]) {
;     ...
;     const bool tie = big && cnt != need;
;     if (tie) {
;       if (cnt <= 128) {
; #pragma unroll
;         for (int i = 0; i < 64; ++i) { const int idx = gt + 128 * i; if (idx < n && uu[i] >= flo && uu[i] < fhi) { const int slot = atomicAdd(&mq[0], 1); clq[slot] = mkcmp(scq[idx], idx); } }
;       } else if (gt == 0) mq[6] = 1;
.Lsel_guard_fb:
	s_mov_b32 s65, 1
	ds_write_b32 v207, v206 offset:24
	s_branch .Lsel_B_done

; __device__ __forceinline__ unsigned xb_ld(unsigned* p)              { return __hip_atomic_load(p, __ATOMIC_RELAXED, __HIP_MEMORY_SCOPE_AGENT); }
; __device__ __forceinline__ unsigned xb_add(unsigned* p, unsigned v) { return __hip_atomic_fetch_add(p, v, __ATOMIC_RELAXED, __HIP_MEMORY_SCOPE_AGENT); }
; #define XB_SPIN(cond, bar) do { unsigned _sp = 0; while (cond) { __builtin_amdgcn_s_sleep(1); \
;     if ((++_sp & 255u) == 0u) { if (xb_ld(&(bar)[XB_TMO])) break; if (_sp > XB_SPIN_CAP) { atomicAdd(&(bar)[XB_TMO], 1u); break; } } } } while (0)
; __device__ __forceinline__ void xcd_barrier(const XcdBarrier& b) {
;     ...
;             else XB_SPIN(xb_ld(&bar[XB_TOPGEN]) == tg, bar);
;             __builtin_amdgcn_fence(__ATOMIC_ACQUIRE, "agent");
;             xb_add(&bar[XB_XGEN(b.x)], 1u);
;             asm volatile("s_waitcnt vmcnt(0)" ::: "memory");
.LBB0_2573:
	s_or_b64 exec, exec, s[6:7]
	s_mov_b64 s[6:7], exec
	v_mbcnt_lo_u32_b32 v0, s6, 0
	v_mbcnt_hi_u32_b32 v0, s7, v0
	v_cmp_eq_u32_e32 vcc, 0, v0
	s_waitcnt vmcnt(0)
	buffer_inv sc1
	s_and_saveexec_b64 s[8:9], vcc
	s_cbranch_execz .LBB0_2575
	s_bcnt1_i32_b64 s6, s[6:7]
	v_mov_b32_e32 v0, 0x2000
	v_mov_b32_e32 v1, s6
	global_atomic_add v0, v1, s[2:3] offset:1024
	s_nop 0
	s_nop 0
	s_nop 0
	s_nop 0
	s_nop 0
